# v22 + 128-row gate unit: LayerNorm gamma/beta loads issued with the unit's first loads (one load latency instead of three)
# speedup vs baseline: 1.0069x; 1.0055x over previous
; #define GASP __attribute__((address_space(1)))
; __device__ __forceinline__ void gate_unit(const Params& p, LAS unsigned char* L, int row0, int n, int g, int sample_b) {
;     ...
;     const int t = tid >> 2, ch = tid & 3; const bool ldr = t < n;
;     f32x4 xv[8], sp[4];
;     if (ldr) { const float* src = GVF + (size_t)(row0 + t) * 512 + g * 128 + ch * 32; const GASP f32x4* sq = (const GASP f32x4*)(GST + (size_t)(row0 + t) * 16);
; #pragma unroll
;         for (int i = 0; i < 8; ++i) xv[i] = *(const GASP f32x4*)(src + 4 * i);
; #pragma unroll
;         for (int i = 0; i < 4; ++i) sp[i] = sq[i]; }
;     ...
;         const float* gp = lng + g * 128 + ch * 32; const float* bp = lnb + g * 128 + ch * 32;
; #pragma unroll
;         for (int i = 0; i < 4; ++i) {
;             const f32x4 ya = (xv[2 * i] - mean) * rstd * *(const GASP f32x4*)(gp + 8 * i) + *(const GASP f32x4*)(bp + 8 * i);
;             const f32x4 yc = (xv[2 * i + 1] - mean) * rstd * *(const GASP f32x4*)(gp + 8 * i + 4) + *(const GASP f32x4*)(bp + 8 * i + 4);
.LBB0_889:
	s_and_b64 vcc, exec, s[6:7]
	s_cbranch_vccz .LBB0_916
	v_mov_b32_e32 v107, v208
	s_movk_i32 s6, 0x80
	v_ashrrev_i32_e32 v104, 2, v107
	v_cmp_gt_i32_e64 s[12:13], s6, v104
	s_movk_i32 s6, 0x7f
	v_readfirstlane_b32 s15, v107
	v_cmp_lt_i32_e32 vcc, s6, v104
	s_and_saveexec_b64 s[6:7], vcc
	s_xor_b64 s[6:7], exec, s[6:7]
	s_lshl_b32 s8, s5, 7
	s_or_saveexec_b64 s[6:7], s[6:7]
	v_and_b32_e32 v105, 3, v107
	s_lshl_b32 s14, s14, 7
	v_mov_b32_e32 v0, s8
	v_lshlrev_b32_e32 v102, 7, v105
	s_xor_b64 exec, exec, s[6:7]
	s_cbranch_execz .LBB0_894
	s_waitcnt vmcnt(7)
	v_add_u32_e32 v2, s14, v104
	v_ashrrev_i32_e32 v3, 31, v2
	v_lshlrev_b64 v[4:5], 11, v[2:3]
	v_lshl_add_u64 v[4:5], s[66:67], 0, v[4:5]
	s_lshl_b32 s30, s5, 9
	v_lshl_add_u64 v[4:5], v[4:5], 0, s[30:31]
	v_mov_b32_e32 v103, v1
	s_waitcnt vmcnt(0)
	v_lshl_add_u64 v[14:15], v[4:5], 0, v[102:103]
	v_lshlrev_b64 v[2:3], 6, v[2:3]
	v_lshl_add_u64 v[16:17], s[64:65], 0, v[2:3]
	global_load_dwordx4 v[18:21], v[14:15], off offset:48
	global_load_dwordx4 v[22:25], v[14:15], off offset:32
	global_load_dwordx4 v[30:33], v[14:15], off offset:16
	global_load_dwordx4 v[62:65], v[14:15], off
	global_load_dwordx4 v[2:5], v[14:15], off offset:112
	global_load_dwordx4 v[6:9], v[14:15], off offset:96
	global_load_dwordx4 v[10:13], v[14:15], off offset:80
	global_load_dwordx4 v[26:29], v[14:15], off offset:64
	global_load_dwordx4 v[66:69], v[16:17], off offset:48
	global_load_dwordx4 v[70:73], v[16:17], off offset:32
	global_load_dwordx4 v[74:77], v[16:17], off offset:16
	global_load_dwordx4 v[78:81], v[16:17], off
	v_readlane_b32 s98, v252, 10
	v_readlane_b32 s99, v252, 11
	v_lshl_add_u32 v250, v0, 2, v102
	global_load_dwordx4 v[128:131], v250, s[18:19]
	global_load_dwordx4 v[132:135], v250, s[18:19] offset:16
	global_load_dwordx4 v[136:139], v250, s[18:19] offset:32
	global_load_dwordx4 v[140:143], v250, s[18:19] offset:48
	global_load_dwordx4 v[144:147], v250, s[18:19] offset:64
	global_load_dwordx4 v[148:151], v250, s[18:19] offset:80
	global_load_dwordx4 v[152:155], v250, s[18:19] offset:96
	global_load_dwordx4 v[156:159], v250, s[18:19] offset:112
	global_load_dwordx4 v[176:179], v250, s[98:99]
	global_load_dwordx4 v[180:183], v250, s[98:99] offset:16
	global_load_dwordx4 v[184:187], v250, s[98:99] offset:32
	global_load_dwordx4 v[188:191], v250, s[98:99] offset:48
	global_load_dwordx4 v[192:195], v250, s[98:99] offset:64
	global_load_dwordx4 v[196:199], v250, s[98:99] offset:80
	global_load_dwordx4 v[200:203], v250, s[98:99] offset:96
	global_load_dwordx4 v[204:207], v250, s[98:99] offset:112
	s_lshl_b32 s5, s5, 7
	v_mov_b32_e32 v0, s5

; #define LAS __attribute__((address_space(3)))
; #define GASP __attribute__((address_space(1)))
; __device__ __forceinline__ void gate_unit(const Params& p, LAS unsigned char* L, int row0, int n, int g, int sample_b) {
;     ...
;     if (active) { const bf16_t* up = UB + (size_t)(row0 + te) * 512 + g * 128 + dh * 64 + 4 * hi; bias = bs[g * 128 + te];
; #pragma unroll
;         for (int i = 0; i < 8; ++i) uu[i] = *(const GASP u32x2*)(up + (i >> 2) * 32 + 8 * (i & 3)); }
;     if (ldr) {
;         float s = 0.f, q = 0.f;
; #pragma unroll
;         for (int i = 0; i < 4; ++i) { s += sp[i][0] + sp[i][2]; q += sp[i][1] + sp[i][3]; }
;         const float mean = s * (1.f / 512.f), rstd = 1.f / sqrtf(q * (1.f / 512.f) - mean * mean + LN_EPS);
;         const float* gp = lng + g * 128 + ch * 32; const float* bp = lnb + g * 128 + ch * 32;
; #pragma unroll
;         for (int i = 0; i < 4; ++i) {
;             const f32x4 ya = (xv[2 * i] - mean) * rstd * *(const GASP f32x4*)(gp + 8 * i) + *(const GASP f32x4*)(bp + 8 * i);
;             const f32x4 yc = (xv[2 * i + 1] - mean) * rstd * *(const GASP f32x4*)(gp + 8 * i + 4) + *(const GASP f32x4*)(bp + 8 * i + 4);
;             u32x4 w; w.x = pk2(ya[0], ya[1]); w.y = pk2(ya[2], ya[3]); w.z = pk2(yc[0], yc[1]); w.w = pk2(yc[2], yc[3]);
;             *(LAS u32x4*)(L + t * DA_VRS + ch * 64 + i * 16) = w;
;             if (sample_b >= 0) { float* o = p.out + OUT_GV + (size_t)(sample_b * 32 + t) * 512 + g * 128 + ch * 32 + 8 * i; *(GASP f32x4*)o = ya; *(GASP f32x4*)(o + 4) = yc; }
;         }
;     }
.LBB0_906:
	v_or_b32_e32 v82, s28, v82
	v_or_b32_e32 v106, s14, v82
	s_ashr_i32 s5, s15, 8
	v_lshlrev_b32_e32 v84, 10, v106
	v_mov_b32_e32 v85, v1
	v_lshl_add_u64 v[84:85], s[60:61], 0, v[84:85]
	s_lshl_b32 s84, s5, 6
	v_lshl_add_u64 v[84:85], v[0:1], 1, v[84:85]
	s_ashr_i32 s85, s84, 31
	v_readlane_b32 s14, v252, 8
	v_lshlrev_b32_e32 v100, 3, v83
	v_lshl_add_u64 v[84:85], s[84:85], 1, v[84:85]
	v_mov_b32_e32 v101, v1
	v_or_b32_e32 v86, v0, v82
	v_mov_b32_e32 v87, v1
	v_readlane_b32 s15, v252, 9
	v_lshl_add_u64 v[84:85], v[84:85], 0, v[100:101]
	s_nop 0
	v_lshl_add_u64 v[86:87], v[86:87], 2, s[14:15]
	global_load_dword v82, v[86:87], off
	global_load_dwordx2 v[98:99], v[84:85], off
	global_load_dwordx2 v[96:97], v[84:85], off offset:16
	global_load_dwordx2 v[94:95], v[84:85], off offset:32
	global_load_dwordx2 v[92:93], v[84:85], off offset:48
	global_load_dwordx2 v[90:91], v[84:85], off offset:64
	global_load_dwordx2 v[88:89], v[84:85], off offset:80
	global_load_dwordx2 v[86:87], v[84:85], off offset:96
	s_nop 0
	global_load_dwordx2 v[84:85], v[84:85], off offset:112
	s_and_saveexec_b64 s[86:87], s[12:13]
	s_cbranch_execz .LBB0_908
	v_pk_add_f32 v[78:79], v[78:79], v[80:81]
	v_pk_add_f32 v[74:75], v[74:75], v[76:77]
	v_pk_add_f32 v[78:79], v[78:79], 0 op_sel_hi:[1,0]
	v_pk_add_f32 v[70:71], v[70:71], v[72:73]
	v_pk_add_f32 v[74:75], v[74:75], v[78:79]
	v_pk_add_f32 v[66:67], v[66:67], v[68:69]
	v_pk_add_f32 v[70:71], v[70:71], v[74:75]
	s_mov_b32 s12, 0x3b000000
	v_pk_add_f32 v[66:67], v[66:67], v[70:71]
	v_mov_b32_e32 v103, v1
	v_pk_mul_f32 v[78:79], v[66:67], s[12:13] op_sel_hi:[1,0]
	s_nop 0
	v_fma_f32 v66, -v78, v78, v79
	v_add_f32_e32 v66, 0x3727c5ac, v66
	v_cmp_gt_f32_e32 vcc, s35, v66
	v_mul_f32_e32 v67, 0x4f800000, v66
	v_sub_f32_e32 v65, v65, v78
	v_cndmask_b32_e32 v66, v66, v67, vcc
	v_sqrt_f32_e32 v67, v66
	v_sub_f32_e32 v64, v64, v78
	v_sub_f32_e32 v63, v63, v78
	v_sub_f32_e32 v62, v62, v78
	v_add_u32_e32 v68, -1, v67
	v_fma_f32 v69, -v68, v67, v66
	v_cmp_ge_f32_e64 s[12:13], 0, v69
	v_add_u32_e32 v69, 1, v67
	v_sub_f32_e32 v33, v33, v78
	v_cndmask_b32_e64 v68, v67, v68, s[12:13]
	v_fma_f32 v67, -v69, v67, v66
	v_cmp_lt_f32_e64 s[12:13], 0, v67
	v_sub_f32_e32 v32, v32, v78
	v_sub_f32_e32 v31, v31, v78
	v_cndmask_b32_e64 v67, v68, v69, s[12:13]
	v_mul_f32_e32 v68, 0x37800000, v67
	v_cndmask_b32_e32 v67, v67, v68, vcc
	v_cmp_class_f32_e32 vcc, v66, v170
	v_sub_f32_e32 v30, v30, v78
	v_sub_f32_e32 v25, v25, v78
	v_cndmask_b32_e32 v66, v67, v66, vcc
	v_div_scale_f32 v67, s[12:13], v66, v66, 1.0
	v_rcp_f32_e32 v68, v67
	v_readlane_b32 s12, v252, 10
	v_readlane_b32 s13, v252, 11
	v_sub_f32_e32 v24, v24, v78
	v_fma_f32 v69, -v67, v68, 1.0
	v_fmac_f32_e32 v68, v69, v68
	v_div_scale_f32 v69, vcc, 1.0, v66, 1.0
	v_mul_f32_e32 v70, v69, v68
	v_fma_f32 v71, -v67, v70, v69
	v_fmac_f32_e32 v70, v71, v68
	v_fma_f32 v67, -v67, v70, v69
	v_div_fmas_f32 v67, v67, v68, v70
	v_lshlrev_b64 v[68:69], 2, v[0:1]
	v_div_fixup_f32 v80, v67, v66, 1.0
	v_lshl_add_u64 v[66:67], s[18:19], 0, v[68:69]
	v_lshl_add_u64 v[68:69], s[12:13], 0, v[68:69]
	v_lshl_add_u64 v[66:67], v[66:67], 0, v[102:103]
	v_lshl_add_u64 v[74:75], v[68:69], 0, v[102:103]
	v_mul_lo_u32 v68, v104, s88
	v_lshlrev_b32_e32 v69, 6, v105
	v_add3_u32 v79, 0, v68, v69
	v_pk_mul_f32 v[72:73], v[62:63], v[80:81] op_sel_hi:[1,0]
	v_pk_mul_f32 v[76:77], v[64:65], v[80:81] op_sel_hi:[1,0]
	v_pk_mul_f32 v[30:31], v[30:31], v[80:81] op_sel_hi:[1,0]
	v_pk_mul_f32 v[32:33], v[32:33], v[80:81] op_sel_hi:[1,0]
	v_sub_f32_e32 v23, v23, v78
	v_sub_f32_e32 v22, v22, v78
	v_sub_f32_e32 v21, v21, v78
	v_sub_f32_e32 v20, v20, v78
	v_sub_f32_e32 v19, v19, v78
	v_sub_f32_e32 v18, v18, v78
	v_pk_mul_f32 v[22:23], v[22:23], v[80:81] op_sel_hi:[1,0]
	v_pk_mul_f32 v[24:25], v[24:25], v[80:81] op_sel_hi:[1,0]
	v_pk_mul_f32 v[18:19], v[18:19], v[80:81] op_sel_hi:[1,0]
	v_pk_mul_f32 v[20:21], v[20:21], v[80:81] op_sel_hi:[1,0]
	v_sub_f32_e32 v13, v13, v78
	v_sub_f32_e32 v12, v12, v78
	v_sub_f32_e32 v11, v11, v78
	v_sub_f32_e32 v10, v10, v78
	v_pk_mul_f32 v[10:11], v[10:11], v[80:81] op_sel_hi:[1,0]
	v_pk_mul_f32 v[12:13], v[12:13], v[80:81] op_sel_hi:[1,0]
	v_sub_f32_e32 v9, v9, v78
	v_sub_f32_e32 v8, v8, v78
	v_sub_f32_e32 v7, v7, v78
	v_sub_f32_e32 v6, v6, v78
	v_sub_f32_e32 v5, v5, v78
	v_sub_f32_e32 v4, v4, v78
	v_sub_f32_e32 v3, v3, v78
	v_sub_f32_e32 v2, v2, v78
	v_pk_mul_f32 v[6:7], v[6:7], v[80:81] op_sel_hi:[1,0]
	v_pk_mul_f32 v[8:9], v[8:9], v[80:81] op_sel_hi:[1,0]
	v_pk_mul_f32 v[2:3], v[2:3], v[80:81] op_sel_hi:[1,0]
	v_pk_mul_f32 v[4:5], v[4:5], v[80:81] op_sel_hi:[1,0]
	v_pk_fma_f32 v[24:25], v[24:25], v[138:139], v[186:187]
	v_pk_fma_f32 v[104:105], v[32:33], v[134:135], v[182:183]
	v_pk_fma_f32 v[76:77], v[76:77], v[130:131], v[178:179]
	v_pk_fma_f32 v[72:73], v[72:73], v[128:129], v[176:177]
	v_pk_fma_f32 v[32:33], v[30:31], v[132:133], v[180:181]
	v_cvt_pk_bf16_f32 v30, v72, v73
	v_cvt_pk_bf16_f32 v31, v76, v77
	v_cvt_pk_bf16_f32 v32, v32, v33
	v_cvt_pk_bf16_f32 v33, v104, v105
	ds_write_b128 v79, v[30:33]
	v_pk_fma_f32 v[22:23], v[22:23], v[136:137], v[184:185]
	v_pk_fma_f32 v[30:31], v[20:21], v[142:143], v[190:191]
	v_pk_fma_f32 v[20:21], v[18:19], v[140:141], v[188:189]
	v_cvt_pk_bf16_f32 v18, v22, v23
	v_cvt_pk_bf16_f32 v19, v24, v25
	v_cvt_pk_bf16_f32 v20, v20, v21
	v_cvt_pk_bf16_f32 v21, v30, v31
	ds_write_b128 v79, v[18:21] offset:16
	v_sub_f32_e32 v19, v29, v78
	v_sub_f32_e32 v18, v28, v78
	v_sub_f32_e32 v21, v27, v78
	v_sub_f32_e32 v20, v26, v78
	v_pk_mul_f32 v[102:103], v[20:21], v[80:81] op_sel_hi:[1,0]
	v_pk_mul_f32 v[104:105], v[18:19], v[80:81] op_sel_hi:[1,0]
	s_nop 0
	s_nop 0
	v_pk_fma_f32 v[8:9], v[8:9], v[154:155], v[202:203]
	v_pk_fma_f32 v[64:65], v[12:13], v[150:151], v[198:199]
	v_pk_fma_f32 v[72:73], v[104:105], v[146:147], v[194:195]
	v_pk_fma_f32 v[70:71], v[102:103], v[144:145], v[192:193]
	v_pk_fma_f32 v[12:13], v[10:11], v[148:149], v[196:197]
	v_cvt_pk_bf16_f32 v10, v70, v71
	v_cvt_pk_bf16_f32 v11, v72, v73
	v_cvt_pk_bf16_f32 v12, v12, v13
	v_cvt_pk_bf16_f32 v13, v64, v65
	ds_write_b128 v79, v[10:13] offset:32
	v_pk_fma_f32 v[6:7], v[6:7], v[152:153], v[200:201]
	v_pk_fma_f32 v[10:11], v[4:5], v[158:159], v[206:207]
	v_pk_fma_f32 v[4:5], v[2:3], v[156:157], v[204:205]
	v_cvt_pk_bf16_f32 v2, v6, v7
	v_cvt_pk_bf16_f32 v3, v8, v9
	v_cvt_pk_bf16_f32 v4, v4, v5
	v_cvt_pk_bf16_f32 v5, v10, v11
	ds_write_b128 v79, v[2:5] offset:48
